# chain: scalar-base LDS-DMA issue + regenerated o-store tail (cvt_pk then DPP neighbour swap + v_perm_b32 select, scalar row bases): fewer VALU per step, same values
# speedup vs baseline: 1.0094x; 1.0094x over previous
; #define LAS __attribute__((address_space(3)))
; #define RD_QD(dst, s0) _Pragma("unroll") for (int s_ = 0; s_ < 4; ++s_) { dst[s_] = *(const LAS bf16x8*)(B + CH_QD + i0 * 256 + (((2 * ((s0) + s_) + hi) ^ (i0 & 15)) << 4)); \
;                 dst[4 + s_] = *(const LAS bf16x8*)(B + CH_QD + i1 * 256 + (((2 * ((s0) + s_) + hi) ^ (i1 & 15)) << 4)); }
; #define DECAY(db_) do { f32x4 dc_[4]; _Pragma("unroll") for (int a4_ = 0; a4_ < 4; ++a4_) dc_[a4_] = *(const LAS f32x4*)(B + CH_DEC + ((db_) * 32 + 8 * a4_ + 4 * hi) * 4); \
;                 _Pragma("unroll") for (int a4_ = 0; a4_ < 4; ++a4_) _Pragma("unroll") for (int b4_ = 0; b4_ < 4; ++b4_) T[db_][a4_ * 4 + b4_] *= dc_[a4_][b4_]; } while (0)
; DI void phase_gla_chain(const Params& P, int l, int task0, int ntask_stride, LAS unsigned char* lds) {
;     ...
;             const int i0 = r32, i1 = 32 + r32; const int vv = wid * 32 + r32;
;             bf16x8 fa[8], fb[8], vf[4];
;             f32x16 o[2]; for (int x = 0; x < 16; ++x) { o[0][x] = 0.f; o[1][x] = 0.f; }
;     ...
;             RD_QD(fa, 0);
; #pragma unroll
;             for (int ks = 0; ks < 4; ++ks) vf[ks] = *(const LAS bf16x8*)(B + CH_VT + vv * 128 + (((2 * ks + hi) ^ ((vv >> 1) & 7)) << 4));
;             __builtin_amdgcn_sched_barrier(0);
;             RD_QD(fb, 4);
;             __builtin_amdgcn_sched_barrier(0);
;             MM_QD(fa, 0);
;             DECAY(0); DECAY(1);
;             __builtin_amdgcn_sched_barrier(0);
; #pragma unroll
;             for (int ks = 0; ks < 4; ++ks) { fa[ks] = *(const LAS bf16x8*)(B + CH_AM + i0 * 128 + (((2 * ks + hi) ^ ((i0 >> 1) & 7)) << 4)); fa[4 + ks] = *(const LAS bf16x8*)(B + CH_AM + i1 * 128 + (((2 * ks + hi) ^ ((i1 >> 1) & 7)) << 4)); }
;             __builtin_amdgcn_sched_barrier(0);
;             MM_QD(fb, 4);
;             DECAY(2); DECAY(3);
;             __builtin_amdgcn_sched_barrier(0);
.LBB0_409:
	s_mul_i32 s92, s92, 0x12400
	s_add_i32 s22, s92, 0
	v_add_u32_e32 v74, s22, v205
	v_add_u32_e32 v75, s22, v141
	v_add_u32_e32 v66, v74, v149
	v_add_u32_e32 v70, v75, v149
	v_add_u32_e32 v76, v74, v151
	ds_read_b128 v[66:69], v66
	ds_read_b128 v[70:73], v70
	v_add_u32_e32 v77, v75, v151
	ds_read_b128 v[182:185], v76
	ds_read_b128 v[186:189], v77
	v_add_u32_e32 v76, v74, v153
	v_add_u32_e32 v77, v75, v153
	ds_read_b128 v[190:193], v76
	ds_read_b128 v[194:197], v77
	v_add_u32_e32 v76, v74, v160
	v_add_u32_e32 v77, v75, v160
	ds_read_b128 v[198:201], v76
	ds_read_b128 v[208:211], v77
	v_add_u32_e32 v76, s22, v173
	v_add_u32_e32 v77, v76, v162
	v_add_u32_e32 v78, v76, v164
	ds_read_b128 v[110:113], v77 offset:40960
	ds_read_b128 v[106:109], v78 offset:40960
	v_add_u32_e32 v77, v76, v165
	v_add_u32_e32 v76, v76, v166
	ds_read_b128 v[102:105], v77 offset:40960
	ds_read_b128 v[98:101], v76 offset:40960
	v_add_u32_e32 v76, v74, v167
	v_add_u32_e32 v77, v75, v167
	ds_read_b128 v[212:215], v76
	ds_read_b128 v[216:219], v77
	v_add_u32_e32 v76, v74, v168
	v_add_u32_e32 v77, v75, v168
	ds_read_b128 v[220:223], v76
	ds_read_b128 v[130:133], v77
	v_add_u32_e32 v76, v74, v169
	v_add_u32_e32 v74, v74, v170
	v_add_u32_e32 v77, v75, v169
	ds_read_b128 v[126:129], v76
	ds_read_b128 v[122:125], v77
	v_add_u32_e32 v75, v75, v170
	ds_read_b128 v[118:121], v74
	ds_read_b128 v[114:117], v75
	v_cvt_pk_bf16_f32 v74, v2, v3
	v_cvt_pk_bf16_f32 v75, v4, v5
	v_cvt_pk_bf16_f32 v76, v6, v7
	v_cvt_pk_bf16_f32 v77, v8, v9
	v_cvt_pk_bf16_f32 v224, v10, v11
	v_cvt_pk_bf16_f32 v225, v12, v13
	s_waitcnt lgkmcnt(0)
	v_mfma_f32_32x32x16_bf16 v[82:97], v[66:69], v[74:77], 0
	v_cvt_pk_bf16_f32 v226, v14, v15
	v_cvt_pk_bf16_f32 v227, v16, v17
	v_add_u32_e32 v207, s22, v146
	v_add_u32_e32 v231, 0x12000, v207
	v_cvt_pk_bf16_f32 v228, v26, v27
	v_cvt_pk_bf16_f32 v229, v28, v29
	v_cvt_pk_bf16_f32 v230, v30, v31
	v_mfma_f32_32x32x16_bf16 v[66:81], v[70:73], v[74:77], 0
	v_mfma_f32_32x32x16_bf16 v[82:97], v[182:185], v[224:227], v[82:97]
	v_cvt_pk_bf16_f32 v182, v18, v19
	v_cvt_pk_bf16_f32 v183, v20, v21
	v_cvt_pk_bf16_f32 v184, v22, v23
	v_cvt_pk_bf16_f32 v185, v24, v25
	v_mfma_f32_32x32x16_bf16 v[66:81], v[186:189], v[224:227], v[66:81]
	ds_read_b128 v[186:189], v231 offset:64
	ds_read_b128 v[224:227], v231 offset:96
	ds_read_b128 v[232:235], v231
	ds_read_b128 v[236:239], v231 offset:32
	v_cvt_pk_bf16_f32 v231, v32, v33
	s_waitcnt lgkmcnt(0)
	v_pk_mul_f32 v[10:11], v[10:11], v[186:187]
	v_pk_mul_f32 v[12:13], v[12:13], v[188:189]
	v_pk_mul_f32 v[14:15], v[14:15], v[224:225]
	v_pk_mul_f32 v[6:7], v[6:7], v[236:237]
	v_pk_mul_f32 v[16:17], v[16:17], v[226:227]
	v_mfma_f32_32x32x16_bf16 v[82:97], v[190:193], v[182:185], v[82:97]
	v_mul_f32_e64 v8, v8, v238
	v_mul_f32_e64 v9, v9, v239
	v_mul_f32_e64 v4, v4, v234
	v_mul_f32_e64 v5, v5, v235
	v_mul_f32_e64 v2, v2, v232
	v_mul_f32_e64 v3, v3, v233
	v_mfma_f32_32x32x16_bf16 v[66:81], v[194:197], v[182:185], v[66:81]
	v_add_u32_e32 v194, 0x12080, v207
	ds_read_b128 v[182:185], v194 offset:64
	ds_read_b128 v[186:189], v194 offset:96
	ds_read_b128 v[190:193], v194
	ds_read_b128 v[194:197], v194 offset:32
	s_waitcnt lgkmcnt(0)
	v_pk_mul_f32 v[26:27], v[26:27], v[182:183]
	v_pk_mul_f32 v[30:31], v[30:31], v[186:187]
	v_pk_mul_f32 v[32:33], v[32:33], v[188:189]
	v_pk_mul_f32 v[22:23], v[22:23], v[194:195]
	v_pk_mul_f32 v[28:29], v[28:29], v[184:185]
	v_pk_mul_f32 v[24:25], v[24:25], v[196:197]
	v_pk_mul_f32 v[20:21], v[20:21], v[192:193]
	v_pk_mul_f32 v[18:19], v[18:19], v[190:191]
	v_mfma_f32_32x32x16_bf16 v[82:97], v[198:201], v[228:231], v[82:97]
	v_mfma_f32_32x32x16_bf16 v[66:81], v[208:211], v[228:231], v[66:81]
	v_add_u32_e32 v224, s22, v143
	v_add_u32_e32 v225, s22, v145
	v_add_u32_e32 v240, v224, v162
	v_add_u32_e32 v186, v225, v162
	v_add_u32_e32 v241, v224, v164
	v_add_u32_e32 v194, v225, v164
	v_add_u32_e32 v242, v224, v165
	v_add_u32_e32 v208, v225, v165
	v_add_u32_e32 v243, v224, v166
	v_add_u32_e32 v228, v225, v166
	ds_read_b128 v[182:185], v240 offset:16384
	ds_read_b128 v[186:189], v186 offset:16384
	ds_read_b128 v[190:193], v241 offset:16384
	ds_read_b128 v[194:197], v194 offset:16384
	ds_read_b128 v[198:201], v242 offset:16384
	ds_read_b128 v[208:211], v208 offset:16384
	ds_read_b128 v[224:227], v243 offset:16384
	ds_read_b128 v[228:231], v228 offset:16384
	v_cvt_pk_bf16_f32 v232, v34, v35
	v_cvt_pk_bf16_f32 v233, v36, v37
	v_cvt_pk_bf16_f32 v234, v38, v39
	v_cvt_pk_bf16_f32 v235, v40, v41
	s_nop 1
	v_mfma_f32_32x32x16_bf16 v[82:97], v[212:215], v[232:235], v[82:97]
	v_cvt_pk_bf16_f32 v212, v42, v43
	v_cvt_pk_bf16_f32 v213, v44, v45
	v_cvt_pk_bf16_f32 v214, v46, v47
	v_cvt_pk_bf16_f32 v215, v48, v49
	v_mfma_f32_32x32x16_bf16 v[66:81], v[216:219], v[232:235], v[66:81]
	v_cvt_pk_bf16_f32 v216, v50, v51
	v_cvt_pk_bf16_f32 v217, v52, v53
	v_cvt_pk_bf16_f32 v218, v54, v55
	v_cvt_pk_bf16_f32 v219, v56, v57
	v_mfma_f32_32x32x16_bf16 v[82:97], v[220:223], v[212:215], v[82:97]
	v_add_u32_e32 v223, 0x12100, v207
	v_add_u32_e32 v207, 0x12180, v207
	v_cvt_pk_bf16_f32 v220, v58, v59
	v_cvt_pk_bf16_f32 v221, v60, v61
	v_cvt_pk_bf16_f32 v222, v62, v63
	v_mfma_f32_32x32x16_bf16 v[66:81], v[130:133], v[212:215], v[66:81]
	ds_read_b128 v[130:133], v223 offset:64
	ds_read_b128 v[212:215], v223 offset:96
	ds_read_b128 v[232:235], v223
	ds_read_b128 v[236:239], v223 offset:32
	v_cvt_pk_bf16_f32 v223, v64, v65
	s_waitcnt lgkmcnt(0)
; #define RD_KT(dst, db0) _Pragma("unroll") for (int q_ = 0; q_ < 2; ++q_) { const int d_ = ((db0) + q_) * 32 + r32; \
;                 _Pragma("unroll") for (int ks_ = 0; ks_ < 4; ++ks_) dst[q_ * 4 + ks_] = *(const LAS bf16x8*)(B + CH_KT + d_ * 128 + (((2 * ks_ + hi) ^ ((d_ >> 1) & 7)) << 4)); }
; #define DECAY(db_) do { f32x4 dc_[4]; _Pragma("unroll") for (int a4_ = 0; a4_ < 4; ++a4_) dc_[a4_] = *(const LAS f32x4*)(B + CH_DEC + ((db_) * 32 + 8 * a4_ + 4 * hi) * 4); \
;                 _Pragma("unroll") for (int a4_ = 0; a4_ < 4; ++a4_) _Pragma("unroll") for (int b4_ = 0; b4_ < 4; ++b4_) T[db_][a4_ * 4 + b4_] *= dc_[a4_][b4_]; } while (0)
; #define MM_KT(src, db0) _Pragma("unroll") for (int q_ = 0; q_ < 2; ++q_) { \
;                 _Pragma("unroll") for (int ks_ = 0; ks_ < 4; ++ks_) T[(db0) + q_] = __builtin_amdgcn_mfma_f32_32x32x16_bf16(src[q_ * 4 + ks_], vf[ks_], T[(db0) + q_], 0, 0, 0); }
; DI void phase_gla_chain(const Params& P, int l, int task0, int ntask_stride, LAS unsigned char* lds) {
;     ...
;             MM_QD(fb, 4);
;             DECAY(2); DECAY(3);
;             __builtin_amdgcn_sched_barrier(0);
;             RD_KT(fb, 0);
;             __builtin_amdgcn_sched_barrier(0);
; #pragma unroll
;             for (int ks = 0; ks < 4; ++ks) { o[0] = __builtin_amdgcn_mfma_f32_32x32x16_bf16(fa[ks], vf[ks], o[0], 0, 0, 0); o[1] = __builtin_amdgcn_mfma_f32_32x32x16_bf16(fa[4 + ks], vf[ks], o[1], 0, 0, 0); }
;             __builtin_amdgcn_sched_barrier(0);
;             RD_KT(fa, 2);
;             __builtin_amdgcn_sched_barrier(0);
;             MM_KT(fb, 0);
;             __builtin_amdgcn_sched_barrier(0);
;             MM_KT(fa, 2);
	v_pk_mul_f32 v[42:43], v[42:43], v[130:131]
	v_pk_mul_f32 v[46:47], v[46:47], v[212:213]
	v_pk_mul_f32 v[48:49], v[48:49], v[214:215]
	v_pk_mul_f32 v[44:45], v[44:45], v[132:133]
	v_pk_mul_f32 v[38:39], v[38:39], v[236:237]
	v_mfma_f32_32x32x16_bf16 v[82:97], v[126:129], v[216:219], v[82:97]
	v_mul_f32_e64 v40, v40, v238
	v_mul_f32_e64 v41, v41, v239
	v_mul_f32_e64 v36, v36, v234
	v_mul_f32_e64 v37, v37, v235
	v_mul_f32_e64 v34, v34, v232
	v_mul_f32_e64 v35, v35, v233
	v_mfma_f32_32x32x16_bf16 v[66:81], v[122:125], v[216:219], v[66:81]
	ds_read_b128 v[122:125], v207 offset:64
	ds_read_b128 v[126:129], v207 offset:96
	ds_read_b128 v[130:133], v207
	ds_read_b128 v[212:215], v207 offset:32
	s_waitcnt lgkmcnt(0)
	v_pk_mul_f32 v[58:59], v[58:59], v[122:123]
	v_pk_mul_f32 v[62:63], v[62:63], v[126:127]
	v_pk_mul_f32 v[64:65], v[64:65], v[128:129]
	v_pk_mul_f32 v[54:55], v[54:55], v[212:213]
	v_pk_mul_f32 v[60:61], v[60:61], v[124:125]
	v_pk_mul_f32 v[56:57], v[56:57], v[214:215]
	v_pk_mul_f32 v[52:53], v[52:53], v[132:133]
	v_pk_mul_f32 v[50:51], v[50:51], v[130:131]
	v_mfma_f32_32x32x16_bf16 v[82:97], v[118:121], v[220:223], v[82:97]
	v_mfma_f32_32x32x16_bf16 v[66:81], v[114:117], v[220:223], v[66:81]
	ds_read_b128 v[114:117], v240 offset:24576
	ds_read_b128 v[118:121], v240 offset:28672
	ds_read_b128 v[122:125], v241 offset:24576
	ds_read_b128 v[126:129], v241 offset:28672
	ds_read_b128 v[130:133], v242 offset:24576
	ds_read_b128 v[212:215], v242 offset:28672
	ds_read_b128 v[216:219], v243 offset:24576
	ds_read_b128 v[220:223], v243 offset:28672
	v_mfma_f32_32x32x16_bf16 v[82:97], v[182:185], v[110:113], v[82:97]
	v_mfma_f32_32x32x16_bf16 v[66:81], v[186:189], v[110:113], v[66:81]
	v_mfma_f32_32x32x16_bf16 v[82:97], v[190:193], v[106:109], v[82:97]
	v_mfma_f32_32x32x16_bf16 v[66:81], v[194:197], v[106:109], v[66:81]
	v_mfma_f32_32x32x16_bf16 v[82:97], v[198:201], v[102:105], v[82:97]
	v_mfma_f32_32x32x16_bf16 v[66:81], v[208:211], v[102:105], v[66:81]
	v_mfma_f32_32x32x16_bf16 v[82:97], v[224:227], v[98:101], v[82:97]
	v_mfma_f32_32x32x16_bf16 v[66:81], v[228:231], v[98:101], v[66:81]
	ds_read_b128 v[182:185], v240 offset:32768
	ds_read_b128 v[186:189], v240 offset:36864
	ds_read_b128 v[190:193], v241 offset:32768
	ds_read_b128 v[194:197], v241 offset:36864
	ds_read_b128 v[198:201], v242 offset:32768
	ds_read_b128 v[208:211], v242 offset:36864
	ds_read_b128 v[224:227], v243 offset:32768
	ds_read_b128 v[228:231], v243 offset:36864
	s_waitcnt lgkmcnt(0)
; DI int crow(int r, int hi) { return (r & 3) + 8 * (r >> 2) + 4 * hi; }
; DI unsigned pkbf(float a, float b) { f32x2 v = {a, b}; bfx2 r = __builtin_convertvector(v, bfx2); return __builtin_bit_cast(unsigned, r); }
; #define MM_KT(src, db0) _Pragma("unroll") for (int q_ = 0; q_ < 2; ++q_) { \
;                 _Pragma("unroll") for (int ks_ = 0; ks_ < 4; ++ks_) T[(db0) + q_] = __builtin_amdgcn_mfma_f32_32x32x16_bf16(src[q_ * 4 + ks_], vf[ks_], T[(db0) + q_], 0, 0, 0); }
; DI void phase_gla_chain(const Params& P, int l, int task0, int ntask_stride, LAS unsigned char* lds) {
;     ...
;             MM_KT(fb, 0);
;             __builtin_amdgcn_sched_barrier(0);
;             MM_KT(fa, 2);
;     ...
;             { const int cs = dir ? 63 - n : n; const size_t tokb = (size_t)sq * SEQL + cs * 64; const int odd = lane & 1;
;               bf16_t* ob = OFB + (size_t)dir * MTOK * 1024 + h * 256 + wid * 32 + (r32 & ~1);
; #pragma unroll
;               for (int ib = 0; ib < 2; ++ib)
; #pragma unroll
;                   for (int x = 0; x < 16; x += 2) { float ea_ = o[ib][x], eb_ = o[ib][x + 1]; asm volatile("" : "+v"(ea_), "+v"(eb_)); const float mine = odd ? eb_ : ea_, give = odd ? ea_ : eb_;
;                       const float got = __int_as_float(__builtin_amdgcn_update_dpp(0, __float_as_int(give), 0xB1, 0xF, 0xF, true));
;                       const unsigned w = odd ? pkbf(got, mine) : pkbf(mine, got);
;                       *(unsigned*)(ob + (tokb + ib * 32 + crow(x + odd, hi)) * 1024) = w; } }
	v_mfma_f32_32x32x16_bf16 v[2:17], v[114:117], v[110:113], v[2:17]
	v_mfma_f32_32x32x16_bf16 v[18:33], v[118:121], v[110:113], v[18:33]
	v_mfma_f32_32x32x16_bf16 v[2:17], v[122:125], v[106:109], v[2:17]
	v_mfma_f32_32x32x16_bf16 v[18:33], v[126:129], v[106:109], v[18:33]
	v_mfma_f32_32x32x16_bf16 v[2:17], v[130:133], v[102:105], v[2:17]
	v_mfma_f32_32x32x16_bf16 v[18:33], v[212:215], v[102:105], v[18:33]
	v_mfma_f32_32x32x16_bf16 v[2:17], v[216:219], v[98:101], v[2:17]
	v_mfma_f32_32x32x16_bf16 v[18:33], v[220:223], v[98:101], v[18:33]
	s_add_i32 s64, s8, 1
	s_and_b64 s[22:23], s[10:11], exec
	s_cselect_b32 s22, s91, s64
	s_lshl_b32 s22, s22, 6
	s_add_u32 s23, s20, s22
	s_addc_u32 s22, s21, 0
	s_add_i32 s8, s8, -1
	s_add_i32 s90, s90, 1
	v_readfirstlane_b32 s98, v158
	v_readfirstlane_b32 s99, v159
	v_and_b32_e32 v244, 30, v137
	v_lshlrev_b32_e32 v244, 1, v244
	v_lshl_add_u32 v244, v136, 11, v244
	v_mov_b32_e32 v252, 0x3020706
	v_mov_b32_e32 v253, 0x5040100
	v_cndmask_b32_e64 v252, v252, v253, s[0:1]
	s_lshl_b32 s100, s23, 11
	s_add_u32 s98, s98, s100
	s_addc_u32 s99, s99, 0
	v_cvt_pk_bf16_f32 v82, v82, v83
	v_cvt_pk_bf16_f32 v84, v84, v85
	v_mfma_f32_32x32x16_bf16 v[34:49], v[182:185], v[110:113], v[34:49]
	s_add_u32 s100, s98, 0x800
	s_addc_u32 s101, s99, 0
	v_mov_b32_dpp v250, v82 quad_perm:[1,0,3,2] row_mask:0xf bank_mask:0xf bound_ctrl:1
	v_mov_b32_dpp v251, v84 quad_perm:[1,0,3,2] row_mask:0xf bank_mask:0xf bound_ctrl:1
	v_perm_b32 v82, v250, v82, v252
	v_perm_b32 v84, v251, v84, v252
	global_store_dword v244, v82, s[100:101] offset:-2048
	global_store_dword v244, v84, s[100:101] offset:2048
	v_cvt_pk_bf16_f32 v86, v86, v87
	v_cvt_pk_bf16_f32 v88, v88, v89
	v_mfma_f32_32x32x16_bf16 v[50:65], v[186:189], v[110:113], v[50:65]
	s_add_u32 s100, s98, 0x4800
	s_addc_u32 s101, s99, 0
	v_mov_b32_dpp v250, v86 quad_perm:[1,0,3,2] row_mask:0xf bank_mask:0xf bound_ctrl:1
	v_mov_b32_dpp v251, v88 quad_perm:[1,0,3,2] row_mask:0xf bank_mask:0xf bound_ctrl:1
	v_perm_b32 v86, v250, v86, v252
	v_perm_b32 v88, v251, v88, v252
	global_store_dword v244, v86, s[100:101] offset:-2048
	global_store_dword v244, v88, s[100:101] offset:2048
	v_cvt_pk_bf16_f32 v90, v90, v91
	v_cvt_pk_bf16_f32 v92, v92, v93
	v_mfma_f32_32x32x16_bf16 v[34:49], v[190:193], v[106:109], v[34:49]
	s_add_u32 s100, s98, 0x8800
	s_addc_u32 s101, s99, 0
	v_mov_b32_dpp v250, v90 quad_perm:[1,0,3,2] row_mask:0xf bank_mask:0xf bound_ctrl:1
	v_mov_b32_dpp v251, v92 quad_perm:[1,0,3,2] row_mask:0xf bank_mask:0xf bound_ctrl:1
	v_perm_b32 v90, v250, v90, v252
	v_perm_b32 v92, v251, v92, v252
	global_store_dword v244, v90, s[100:101] offset:-2048
	global_store_dword v244, v92, s[100:101] offset:2048
	v_cvt_pk_bf16_f32 v94, v94, v95
	v_cvt_pk_bf16_f32 v96, v96, v97
	v_mfma_f32_32x32x16_bf16 v[50:65], v[194:197], v[106:109], v[50:65]
	s_add_u32 s100, s98, 0xc800
	s_addc_u32 s101, s99, 0
	v_mov_b32_dpp v250, v94 quad_perm:[1,0,3,2] row_mask:0xf bank_mask:0xf bound_ctrl:1
	v_mov_b32_dpp v251, v96 quad_perm:[1,0,3,2] row_mask:0xf bank_mask:0xf bound_ctrl:1
	v_perm_b32 v94, v250, v94, v252
	v_perm_b32 v96, v251, v96, v252
	global_store_dword v244, v94, s[100:101] offset:-2048
	global_store_dword v244, v96, s[100:101] offset:2048
	v_cvt_pk_bf16_f32 v66, v66, v67
	v_cvt_pk_bf16_f32 v68, v68, v69
	v_mfma_f32_32x32x16_bf16 v[34:49], v[198:201], v[102:105], v[34:49]
	s_add_u32 s100, s98, 0x10800
	s_addc_u32 s101, s99, 0
	v_mov_b32_dpp v250, v66 quad_perm:[1,0,3,2] row_mask:0xf bank_mask:0xf bound_ctrl:1
	v_mov_b32_dpp v251, v68 quad_perm:[1,0,3,2] row_mask:0xf bank_mask:0xf bound_ctrl:1
	v_perm_b32 v66, v250, v66, v252
	v_perm_b32 v68, v251, v68, v252
	global_store_dword v244, v66, s[100:101] offset:-2048
	global_store_dword v244, v68, s[100:101] offset:2048
	v_cvt_pk_bf16_f32 v70, v70, v71
	v_cvt_pk_bf16_f32 v72, v72, v73
	v_mfma_f32_32x32x16_bf16 v[50:65], v[208:211], v[102:105], v[50:65]
	s_add_u32 s100, s98, 0x14800
	s_addc_u32 s101, s99, 0
	v_mov_b32_dpp v250, v70 quad_perm:[1,0,3,2] row_mask:0xf bank_mask:0xf bound_ctrl:1
	v_mov_b32_dpp v251, v72 quad_perm:[1,0,3,2] row_mask:0xf bank_mask:0xf bound_ctrl:1
	v_perm_b32 v70, v250, v70, v252
	v_perm_b32 v72, v251, v72, v252
	global_store_dword v244, v70, s[100:101] offset:-2048
	global_store_dword v244, v72, s[100:101] offset:2048
	v_cvt_pk_bf16_f32 v74, v74, v75
	v_cvt_pk_bf16_f32 v76, v76, v77
	v_mfma_f32_32x32x16_bf16 v[34:49], v[224:227], v[98:101], v[34:49]
	s_add_u32 s100, s98, 0x18800
	s_addc_u32 s101, s99, 0
	v_mov_b32_dpp v250, v74 quad_perm:[1,0,3,2] row_mask:0xf bank_mask:0xf bound_ctrl:1
	v_mov_b32_dpp v251, v76 quad_perm:[1,0,3,2] row_mask:0xf bank_mask:0xf bound_ctrl:1
	v_perm_b32 v74, v250, v74, v252
	v_perm_b32 v76, v251, v76, v252
	global_store_dword v244, v74, s[100:101] offset:-2048
	global_store_dword v244, v76, s[100:101] offset:2048
	v_cvt_pk_bf16_f32 v78, v78, v79
	v_cvt_pk_bf16_f32 v80, v80, v81
	v_mfma_f32_32x32x16_bf16 v[50:65], v[228:231], v[98:101], v[50:65]
	s_add_u32 s100, s98, 0x1c800
	s_addc_u32 s101, s99, 0
	v_mov_b32_dpp v250, v78 quad_perm:[1,0,3,2] row_mask:0xf bank_mask:0xf bound_ctrl:1
	v_mov_b32_dpp v251, v80 quad_perm:[1,0,3,2] row_mask:0xf bank_mask:0xf bound_ctrl:1
	v_perm_b32 v78, v250, v78, v252
	v_perm_b32 v80, v251, v80, v252
	global_store_dword v244, v78, s[100:101] offset:-2048
	global_store_dword v244, v80, s[100:101] offset:2048
	s_cmp_eq_u32 s8, -2
	s_cbranch_scc1 .LBB0_403

; #define LAS __attribute__((address_space(3)))
; #define RD_QD(dst, s0) _Pragma("unroll") for (int s_ = 0; s_ < 4; ++s_) { dst[s_] = *(const LAS bf16x8*)(B + CH_QD + i0 * 256 + (((2 * ((s0) + s_) + hi) ^ (i0 & 15)) << 4)); \
;                 dst[4 + s_] = *(const LAS bf16x8*)(B + CH_QD + i1 * 256 + (((2 * ((s0) + s_) + hi) ^ (i1 & 15)) << 4)); }
; #define DECAY(db_) do { f32x4 dc_[4]; _Pragma("unroll") for (int a4_ = 0; a4_ < 4; ++a4_) dc_[a4_] = *(const LAS f32x4*)(B + CH_DEC + ((db_) * 32 + 8 * a4_ + 4 * hi) * 4); \
;                 _Pragma("unroll") for (int a4_ = 0; a4_ < 4; ++a4_) _Pragma("unroll") for (int b4_ = 0; b4_ < 4; ++b4_) T[db_][a4_ * 4 + b4_] *= dc_[a4_][b4_]; } while (0)
; DI void phase_gla_chain(const Params& P, int l, int task0, int ntask_stride, LAS unsigned char* lds) {
;     ...
;             const int i0 = r32, i1 = 32 + r32; const int vv = wid * 32 + r32;
;             bf16x8 fa[8], fb[8], vf[4];
;             f32x16 o[2]; for (int x = 0; x < 16; ++x) { o[0][x] = 0.f; o[1][x] = 0.f; }
;     ...
;             RD_QD(fa, 0);
; #pragma unroll
;             for (int ks = 0; ks < 4; ++ks) vf[ks] = *(const LAS bf16x8*)(B + CH_VT + vv * 128 + (((2 * ks + hi) ^ ((vv >> 1) & 7)) << 4));
;             __builtin_amdgcn_sched_barrier(0);
;             RD_QD(fb, 4);
;             __builtin_amdgcn_sched_barrier(0);
;             MM_QD(fa, 0);
;             DECAY(0); DECAY(1);
;             __builtin_amdgcn_sched_barrier(0);
; #pragma unroll
;             for (int ks = 0; ks < 4; ++ks) { fa[ks] = *(const LAS bf16x8*)(B + CH_AM + i0 * 128 + (((2 * ks + hi) ^ ((i0 >> 1) & 7)) << 4)); fa[4 + ks] = *(const LAS bf16x8*)(B + CH_AM + i1 * 128 + (((2 * ks + hi) ^ ((i1 >> 1) & 7)) << 4)); }
;             __builtin_amdgcn_sched_barrier(0);
;             MM_QD(fb, 4);
;             DECAY(2); DECAY(3);
;             __builtin_amdgcn_sched_barrier(0);
.LBB0_971:
	s_mul_i32 s84, s84, 0x12400
	s_add_i32 s22, s84, 0
	v_add_u32_e32 v74, s22, v201
	v_add_u32_e32 v75, s22, v141
	v_add_u32_e32 v66, v74, v149
	v_add_u32_e32 v70, v75, v149
	v_add_u32_e32 v76, v74, v151
	ds_read_b128 v[66:69], v66
	ds_read_b128 v[70:73], v70
	v_add_u32_e32 v77, v75, v151
	ds_read_b128 v[182:185], v76
	ds_read_b128 v[186:189], v77
	v_add_u32_e32 v76, v74, v153
	v_add_u32_e32 v77, v75, v153
	ds_read_b128 v[190:193], v76
	ds_read_b128 v[194:197], v77
	v_add_u32_e32 v76, v74, v160
	v_add_u32_e32 v77, v75, v160
	ds_read_b128 v[204:207], v76
	ds_read_b128 v[208:211], v77
	v_add_u32_e32 v76, s22, v173
	v_add_u32_e32 v77, v76, v162
	v_add_u32_e32 v78, v76, v164
	ds_read_b128 v[110:113], v77 offset:40960
	ds_read_b128 v[106:109], v78 offset:40960
	v_add_u32_e32 v77, v76, v165
	v_add_u32_e32 v76, v76, v166
	ds_read_b128 v[102:105], v77 offset:40960
	ds_read_b128 v[98:101], v76 offset:40960
	v_add_u32_e32 v76, v74, v167
	v_add_u32_e32 v77, v75, v167
	ds_read_b128 v[212:215], v76
	ds_read_b128 v[216:219], v77
	v_add_u32_e32 v76, v74, v168
	v_add_u32_e32 v77, v75, v168
	ds_read_b128 v[220:223], v76
	ds_read_b128 v[130:133], v77
	v_add_u32_e32 v76, v74, v169
	v_add_u32_e32 v74, v74, v170
	v_add_u32_e32 v77, v75, v169
	ds_read_b128 v[126:129], v76
	ds_read_b128 v[122:125], v77
	v_add_u32_e32 v75, v75, v170
	ds_read_b128 v[118:121], v74
	ds_read_b128 v[114:117], v75
	v_cvt_pk_bf16_f32 v74, v2, v3
	v_cvt_pk_bf16_f32 v75, v4, v5
	v_cvt_pk_bf16_f32 v76, v6, v7
	v_cvt_pk_bf16_f32 v77, v8, v9
	v_cvt_pk_bf16_f32 v224, v10, v11
	v_cvt_pk_bf16_f32 v225, v12, v13
	s_waitcnt lgkmcnt(0)
	v_mfma_f32_32x32x16_bf16 v[82:97], v[66:69], v[74:77], 0
	v_cvt_pk_bf16_f32 v226, v14, v15
	v_cvt_pk_bf16_f32 v227, v16, v17
	v_add_u32_e32 v198, s22, v146
	v_add_u32_e32 v199, 0x12000, v198
	v_cvt_pk_bf16_f32 v228, v26, v27
	v_cvt_pk_bf16_f32 v229, v28, v29
	v_cvt_pk_bf16_f32 v230, v30, v31
	v_mfma_f32_32x32x16_bf16 v[66:81], v[70:73], v[74:77], 0
	v_cvt_pk_bf16_f32 v231, v32, v33
	v_mfma_f32_32x32x16_bf16 v[82:97], v[182:185], v[224:227], v[82:97]
	v_cvt_pk_bf16_f32 v182, v18, v19
	v_cvt_pk_bf16_f32 v183, v20, v21
	v_cvt_pk_bf16_f32 v184, v22, v23
	v_cvt_pk_bf16_f32 v185, v24, v25
	v_mfma_f32_32x32x16_bf16 v[66:81], v[186:189], v[224:227], v[66:81]
	ds_read_b128 v[186:189], v199 offset:64
	ds_read_b128 v[224:227], v199 offset:96
	ds_read_b128 v[232:235], v199
	ds_read_b128 v[236:239], v199 offset:32
	s_waitcnt lgkmcnt(0)
	v_pk_mul_f32 v[10:11], v[10:11], v[186:187]
	v_pk_mul_f32 v[12:13], v[12:13], v[188:189]
	v_pk_mul_f32 v[14:15], v[14:15], v[224:225]
	v_pk_mul_f32 v[6:7], v[6:7], v[236:237]
	v_pk_mul_f32 v[16:17], v[16:17], v[226:227]
	v_mfma_f32_32x32x16_bf16 v[82:97], v[190:193], v[182:185], v[82:97]
	v_mul_f32_e64 v8, v8, v238
	v_mul_f32_e64 v9, v9, v239
	v_mul_f32_e64 v4, v4, v234
	v_mul_f32_e64 v5, v5, v235
	v_mul_f32_e64 v2, v2, v232
	v_mul_f32_e64 v3, v3, v233
	v_mfma_f32_32x32x16_bf16 v[66:81], v[194:197], v[182:185], v[66:81]
	v_add_u32_e32 v194, 0x12080, v198
	ds_read_b128 v[182:185], v194 offset:64
	ds_read_b128 v[186:189], v194 offset:96
	ds_read_b128 v[190:193], v194
	ds_read_b128 v[194:197], v194 offset:32
	s_waitcnt lgkmcnt(0)
	v_pk_mul_f32 v[26:27], v[26:27], v[182:183]
	v_pk_mul_f32 v[30:31], v[30:31], v[186:187]
	v_pk_mul_f32 v[32:33], v[32:33], v[188:189]
	v_pk_mul_f32 v[22:23], v[22:23], v[194:195]
	v_pk_mul_f32 v[28:29], v[28:29], v[184:185]
	v_pk_mul_f32 v[24:25], v[24:25], v[196:197]
	v_pk_mul_f32 v[20:21], v[20:21], v[192:193]
	v_pk_mul_f32 v[18:19], v[18:19], v[190:191]
	v_mfma_f32_32x32x16_bf16 v[82:97], v[204:207], v[228:231], v[82:97]
	v_mfma_f32_32x32x16_bf16 v[66:81], v[208:211], v[228:231], v[66:81]
	v_add_u32_e32 v199, s22, v143
	v_add_u32_e32 v224, s22, v145
	v_add_u32_e32 v240, v199, v162
	v_add_u32_e32 v186, v224, v162
	v_add_u32_e32 v241, v199, v164
	v_add_u32_e32 v194, v224, v164
	v_add_u32_e32 v242, v199, v165
	v_add_u32_e32 v208, v224, v165
	v_add_u32_e32 v199, v199, v166
	v_add_u32_e32 v228, v224, v166
	ds_read_b128 v[182:185], v240 offset:16384
	ds_read_b128 v[186:189], v186 offset:16384
	ds_read_b128 v[190:193], v241 offset:16384
	ds_read_b128 v[194:197], v194 offset:16384
	ds_read_b128 v[204:207], v242 offset:16384
	ds_read_b128 v[208:211], v208 offset:16384
	ds_read_b128 v[224:227], v199 offset:16384
	ds_read_b128 v[228:231], v228 offset:16384
	v_cvt_pk_bf16_f32 v232, v34, v35
	v_cvt_pk_bf16_f32 v233, v36, v37
	v_cvt_pk_bf16_f32 v234, v38, v39
	v_cvt_pk_bf16_f32 v235, v40, v41
	s_nop 1
	v_mfma_f32_32x32x16_bf16 v[82:97], v[212:215], v[232:235], v[82:97]
	v_cvt_pk_bf16_f32 v212, v42, v43
	v_cvt_pk_bf16_f32 v213, v44, v45
	v_cvt_pk_bf16_f32 v214, v46, v47
	v_cvt_pk_bf16_f32 v215, v48, v49
	v_mfma_f32_32x32x16_bf16 v[66:81], v[216:219], v[232:235], v[66:81]
	v_cvt_pk_bf16_f32 v216, v50, v51
	v_cvt_pk_bf16_f32 v217, v52, v53
	v_cvt_pk_bf16_f32 v218, v54, v55
	v_cvt_pk_bf16_f32 v219, v56, v57
	v_mfma_f32_32x32x16_bf16 v[82:97], v[220:223], v[212:215], v[82:97]
	v_add_u32_e32 v223, 0x12100, v198
	v_add_u32_e32 v198, 0x12180, v198
	v_cvt_pk_bf16_f32 v220, v58, v59
	v_cvt_pk_bf16_f32 v221, v60, v61
	v_cvt_pk_bf16_f32 v222, v62, v63
	v_mfma_f32_32x32x16_bf16 v[66:81], v[130:133], v[212:215], v[66:81]
	ds_read_b128 v[130:133], v223 offset:64
	ds_read_b128 v[212:215], v223 offset:96
	ds_read_b128 v[232:235], v223
	ds_read_b128 v[236:239], v223 offset:32
	v_cvt_pk_bf16_f32 v223, v64, v65
	s_waitcnt lgkmcnt(0)
; #define RD_KT(dst, db0) _Pragma("unroll") for (int q_ = 0; q_ < 2; ++q_) { const int d_ = ((db0) + q_) * 32 + r32; \
;                 _Pragma("unroll") for (int ks_ = 0; ks_ < 4; ++ks_) dst[q_ * 4 + ks_] = *(const LAS bf16x8*)(B + CH_KT + d_ * 128 + (((2 * ks_ + hi) ^ ((d_ >> 1) & 7)) << 4)); }
; #define DECAY(db_) do { f32x4 dc_[4]; _Pragma("unroll") for (int a4_ = 0; a4_ < 4; ++a4_) dc_[a4_] = *(const LAS f32x4*)(B + CH_DEC + ((db_) * 32 + 8 * a4_ + 4 * hi) * 4); \
;                 _Pragma("unroll") for (int a4_ = 0; a4_ < 4; ++a4_) _Pragma("unroll") for (int b4_ = 0; b4_ < 4; ++b4_) T[db_][a4_ * 4 + b4_] *= dc_[a4_][b4_]; } while (0)
; #define MM_KT(src, db0) _Pragma("unroll") for (int q_ = 0; q_ < 2; ++q_) { \
;                 _Pragma("unroll") for (int ks_ = 0; ks_ < 4; ++ks_) T[(db0) + q_] = __builtin_amdgcn_mfma_f32_32x32x16_bf16(src[q_ * 4 + ks_], vf[ks_], T[(db0) + q_], 0, 0, 0); }
; DI void phase_gla_chain(const Params& P, int l, int task0, int ntask_stride, LAS unsigned char* lds) {
;     ...
;             MM_QD(fb, 4);
;             DECAY(2); DECAY(3);
;             __builtin_amdgcn_sched_barrier(0);
;             RD_KT(fb, 0);
;             __builtin_amdgcn_sched_barrier(0);
; #pragma unroll
;             for (int ks = 0; ks < 4; ++ks) { o[0] = __builtin_amdgcn_mfma_f32_32x32x16_bf16(fa[ks], vf[ks], o[0], 0, 0, 0); o[1] = __builtin_amdgcn_mfma_f32_32x32x16_bf16(fa[4 + ks], vf[ks], o[1], 0, 0, 0); }
;             __builtin_amdgcn_sched_barrier(0);
;             RD_KT(fa, 2);
;             __builtin_amdgcn_sched_barrier(0);
;             MM_KT(fb, 0);
;             __builtin_amdgcn_sched_barrier(0);
;             MM_KT(fa, 2);
	v_pk_mul_f32 v[42:43], v[42:43], v[130:131]
	v_pk_mul_f32 v[46:47], v[46:47], v[212:213]
	v_pk_mul_f32 v[48:49], v[48:49], v[214:215]
	v_pk_mul_f32 v[44:45], v[44:45], v[132:133]
	v_pk_mul_f32 v[38:39], v[38:39], v[236:237]
	v_mfma_f32_32x32x16_bf16 v[82:97], v[126:129], v[216:219], v[82:97]
	v_mul_f32_e64 v40, v40, v238
	v_mul_f32_e64 v41, v41, v239
	v_mul_f32_e64 v36, v36, v234
	v_mul_f32_e64 v37, v37, v235
	v_mul_f32_e64 v34, v34, v232
	v_mul_f32_e64 v35, v35, v233
	v_mfma_f32_32x32x16_bf16 v[66:81], v[122:125], v[216:219], v[66:81]
	ds_read_b128 v[122:125], v198 offset:64
	ds_read_b128 v[126:129], v198 offset:96
	ds_read_b128 v[130:133], v198
	ds_read_b128 v[212:215], v198 offset:32
	s_waitcnt lgkmcnt(0)
	v_pk_mul_f32 v[58:59], v[58:59], v[122:123]
	v_pk_mul_f32 v[62:63], v[62:63], v[126:127]
	v_pk_mul_f32 v[64:65], v[64:65], v[128:129]
	v_pk_mul_f32 v[54:55], v[54:55], v[212:213]
	v_pk_mul_f32 v[60:61], v[60:61], v[124:125]
	v_pk_mul_f32 v[56:57], v[56:57], v[214:215]
	v_pk_mul_f32 v[52:53], v[52:53], v[132:133]
	v_pk_mul_f32 v[50:51], v[50:51], v[130:131]
	v_mfma_f32_32x32x16_bf16 v[82:97], v[118:121], v[220:223], v[82:97]
	v_mfma_f32_32x32x16_bf16 v[66:81], v[114:117], v[220:223], v[66:81]
	ds_read_b128 v[114:117], v240 offset:24576
	ds_read_b128 v[118:121], v240 offset:28672
	ds_read_b128 v[122:125], v241 offset:24576
	ds_read_b128 v[126:129], v241 offset:28672
	ds_read_b128 v[130:133], v242 offset:24576
	ds_read_b128 v[212:215], v242 offset:28672
	ds_read_b128 v[216:219], v199 offset:24576
	ds_read_b128 v[220:223], v199 offset:28672
	v_mfma_f32_32x32x16_bf16 v[82:97], v[182:185], v[110:113], v[82:97]
	v_mfma_f32_32x32x16_bf16 v[66:81], v[186:189], v[110:113], v[66:81]
	v_mfma_f32_32x32x16_bf16 v[82:97], v[190:193], v[106:109], v[82:97]
	v_mfma_f32_32x32x16_bf16 v[66:81], v[194:197], v[106:109], v[66:81]
	v_mfma_f32_32x32x16_bf16 v[82:97], v[204:207], v[102:105], v[82:97]
	v_mfma_f32_32x32x16_bf16 v[66:81], v[208:211], v[102:105], v[66:81]
	v_mfma_f32_32x32x16_bf16 v[82:97], v[224:227], v[98:101], v[82:97]
	v_mfma_f32_32x32x16_bf16 v[66:81], v[228:231], v[98:101], v[66:81]
	ds_read_b128 v[182:185], v240 offset:32768
	ds_read_b128 v[186:189], v240 offset:36864
	ds_read_b128 v[190:193], v241 offset:32768
	ds_read_b128 v[194:197], v241 offset:36864
	ds_read_b128 v[204:207], v242 offset:32768
	ds_read_b128 v[208:211], v242 offset:36864
	ds_read_b128 v[224:227], v199 offset:32768
	ds_read_b128 v[228:231], v199 offset:36864
	s_waitcnt lgkmcnt(0)
; DI int crow(int r, int hi) { return (r & 3) + 8 * (r >> 2) + 4 * hi; }
; DI unsigned pkbf(float a, float b) { f32x2 v = {a, b}; bfx2 r = __builtin_convertvector(v, bfx2); return __builtin_bit_cast(unsigned, r); }
; #define MM_KT(src, db0) _Pragma("unroll") for (int q_ = 0; q_ < 2; ++q_) { \
;                 _Pragma("unroll") for (int ks_ = 0; ks_ < 4; ++ks_) T[(db0) + q_] = __builtin_amdgcn_mfma_f32_32x32x16_bf16(src[q_ * 4 + ks_], vf[ks_], T[(db0) + q_], 0, 0, 0); }
; DI void phase_gla_chain(const Params& P, int l, int task0, int ntask_stride, LAS unsigned char* lds) {
;     ...
;             MM_KT(fb, 0);
;             __builtin_amdgcn_sched_barrier(0);
;             MM_KT(fa, 2);
;     ...
;             { const int cs = dir ? 63 - n : n; const size_t tokb = (size_t)sq * SEQL + cs * 64; const int odd = lane & 1;
;               bf16_t* ob = OFB + (size_t)dir * MTOK * 1024 + h * 256 + wid * 32 + (r32 & ~1);
; #pragma unroll
;               for (int ib = 0; ib < 2; ++ib)
; #pragma unroll
;                   for (int x = 0; x < 16; x += 2) { float ea_ = o[ib][x], eb_ = o[ib][x + 1]; asm volatile("" : "+v"(ea_), "+v"(eb_)); const float mine = odd ? eb_ : ea_, give = odd ? ea_ : eb_;
;                       const float got = __int_as_float(__builtin_amdgcn_update_dpp(0, __float_as_int(give), 0xB1, 0xF, 0xF, true));
;                       const unsigned w = odd ? pkbf(got, mine) : pkbf(mine, got);
;                       *(unsigned*)(ob + (tokb + ib * 32 + crow(x + odd, hi)) * 1024) = w; } }
	v_mfma_f32_32x32x16_bf16 v[2:17], v[114:117], v[110:113], v[2:17]
	v_mfma_f32_32x32x16_bf16 v[18:33], v[118:121], v[110:113], v[18:33]
	v_mfma_f32_32x32x16_bf16 v[2:17], v[122:125], v[106:109], v[2:17]
	v_mfma_f32_32x32x16_bf16 v[18:33], v[126:129], v[106:109], v[18:33]
	v_mfma_f32_32x32x16_bf16 v[2:17], v[130:133], v[102:105], v[2:17]
	v_mfma_f32_32x32x16_bf16 v[18:33], v[212:215], v[102:105], v[18:33]
	v_mfma_f32_32x32x16_bf16 v[2:17], v[216:219], v[98:101], v[2:17]
	v_mfma_f32_32x32x16_bf16 v[18:33], v[220:223], v[98:101], v[18:33]
	s_add_i32 s64, s8, 1
	s_and_b64 s[22:23], s[10:11], exec
	s_cselect_b32 s22, s83, s64
	s_lshl_b32 s22, s22, 6
	s_add_u32 s23, s20, s22
	s_addc_u32 s22, s21, 0
	s_add_i32 s8, s8, -1
	s_add_i32 s82, s82, 1
	v_readfirstlane_b32 s98, v158
	v_readfirstlane_b32 s99, v159
	v_and_b32_e32 v244, 30, v137
	v_lshlrev_b32_e32 v244, 1, v244
	v_lshl_add_u32 v244, v136, 11, v244
	v_mov_b32_e32 v252, 0x3020706
	v_mov_b32_e32 v253, 0x5040100
	v_cndmask_b32_e64 v252, v252, v253, s[0:1]
	s_lshl_b32 s100, s23, 11
	s_add_u32 s98, s98, s100
	s_addc_u32 s99, s99, 0
	v_cvt_pk_bf16_f32 v82, v82, v83
	v_cvt_pk_bf16_f32 v84, v84, v85
	v_mfma_f32_32x32x16_bf16 v[34:49], v[182:185], v[110:113], v[34:49]
	s_add_u32 s100, s98, 0x800
	s_addc_u32 s101, s99, 0
	v_mov_b32_dpp v250, v82 quad_perm:[1,0,3,2] row_mask:0xf bank_mask:0xf bound_ctrl:1
	v_mov_b32_dpp v251, v84 quad_perm:[1,0,3,2] row_mask:0xf bank_mask:0xf bound_ctrl:1
	v_perm_b32 v82, v250, v82, v252
	v_perm_b32 v84, v251, v84, v252
	global_store_dword v244, v82, s[100:101] offset:-2048
	global_store_dword v244, v84, s[100:101] offset:2048
	v_cvt_pk_bf16_f32 v86, v86, v87
	v_cvt_pk_bf16_f32 v88, v88, v89
	v_mfma_f32_32x32x16_bf16 v[50:65], v[186:189], v[110:113], v[50:65]
	s_add_u32 s100, s98, 0x4800
	s_addc_u32 s101, s99, 0
	v_mov_b32_dpp v250, v86 quad_perm:[1,0,3,2] row_mask:0xf bank_mask:0xf bound_ctrl:1
	v_mov_b32_dpp v251, v88 quad_perm:[1,0,3,2] row_mask:0xf bank_mask:0xf bound_ctrl:1
	v_perm_b32 v86, v250, v86, v252
	v_perm_b32 v88, v251, v88, v252
	global_store_dword v244, v86, s[100:101] offset:-2048
	global_store_dword v244, v88, s[100:101] offset:2048
	v_cvt_pk_bf16_f32 v90, v90, v91
	v_cvt_pk_bf16_f32 v92, v92, v93
	v_mfma_f32_32x32x16_bf16 v[34:49], v[190:193], v[106:109], v[34:49]
	s_add_u32 s100, s98, 0x8800
	s_addc_u32 s101, s99, 0
	v_mov_b32_dpp v250, v90 quad_perm:[1,0,3,2] row_mask:0xf bank_mask:0xf bound_ctrl:1
	v_mov_b32_dpp v251, v92 quad_perm:[1,0,3,2] row_mask:0xf bank_mask:0xf bound_ctrl:1
	v_perm_b32 v90, v250, v90, v252
	v_perm_b32 v92, v251, v92, v252
	global_store_dword v244, v90, s[100:101] offset:-2048
	global_store_dword v244, v92, s[100:101] offset:2048
	v_cvt_pk_bf16_f32 v94, v94, v95
	v_cvt_pk_bf16_f32 v96, v96, v97
	v_mfma_f32_32x32x16_bf16 v[50:65], v[194:197], v[106:109], v[50:65]
	s_add_u32 s100, s98, 0xc800
	s_addc_u32 s101, s99, 0
	v_mov_b32_dpp v250, v94 quad_perm:[1,0,3,2] row_mask:0xf bank_mask:0xf bound_ctrl:1
	v_mov_b32_dpp v251, v96 quad_perm:[1,0,3,2] row_mask:0xf bank_mask:0xf bound_ctrl:1
	v_perm_b32 v94, v250, v94, v252
	v_perm_b32 v96, v251, v96, v252
	global_store_dword v244, v94, s[100:101] offset:-2048
	global_store_dword v244, v96, s[100:101] offset:2048
	v_cvt_pk_bf16_f32 v66, v66, v67
	v_cvt_pk_bf16_f32 v68, v68, v69
	v_mfma_f32_32x32x16_bf16 v[34:49], v[204:207], v[102:105], v[34:49]
	s_add_u32 s100, s98, 0x10800
	s_addc_u32 s101, s99, 0
	v_mov_b32_dpp v250, v66 quad_perm:[1,0,3,2] row_mask:0xf bank_mask:0xf bound_ctrl:1
	v_mov_b32_dpp v251, v68 quad_perm:[1,0,3,2] row_mask:0xf bank_mask:0xf bound_ctrl:1
	v_perm_b32 v66, v250, v66, v252
	v_perm_b32 v68, v251, v68, v252
	global_store_dword v244, v66, s[100:101] offset:-2048
	global_store_dword v244, v68, s[100:101] offset:2048
	v_cvt_pk_bf16_f32 v70, v70, v71
	v_cvt_pk_bf16_f32 v72, v72, v73
	v_mfma_f32_32x32x16_bf16 v[50:65], v[208:211], v[102:105], v[50:65]
	s_add_u32 s100, s98, 0x14800
	s_addc_u32 s101, s99, 0
	v_mov_b32_dpp v250, v70 quad_perm:[1,0,3,2] row_mask:0xf bank_mask:0xf bound_ctrl:1
	v_mov_b32_dpp v251, v72 quad_perm:[1,0,3,2] row_mask:0xf bank_mask:0xf bound_ctrl:1
	v_perm_b32 v70, v250, v70, v252
	v_perm_b32 v72, v251, v72, v252
	global_store_dword v244, v70, s[100:101] offset:-2048
	global_store_dword v244, v72, s[100:101] offset:2048
	v_cvt_pk_bf16_f32 v74, v74, v75
	v_cvt_pk_bf16_f32 v76, v76, v77
	v_mfma_f32_32x32x16_bf16 v[34:49], v[224:227], v[98:101], v[34:49]
	s_add_u32 s100, s98, 0x18800
	s_addc_u32 s101, s99, 0
	v_mov_b32_dpp v250, v74 quad_perm:[1,0,3,2] row_mask:0xf bank_mask:0xf bound_ctrl:1
	v_mov_b32_dpp v251, v76 quad_perm:[1,0,3,2] row_mask:0xf bank_mask:0xf bound_ctrl:1
	v_perm_b32 v74, v250, v74, v252
	v_perm_b32 v76, v251, v76, v252
	global_store_dword v244, v74, s[100:101] offset:-2048
	global_store_dword v244, v76, s[100:101] offset:2048
	v_cvt_pk_bf16_f32 v78, v78, v79
	v_cvt_pk_bf16_f32 v80, v80, v81
	v_mfma_f32_32x32x16_bf16 v[50:65], v[228:231], v[98:101], v[50:65]
	s_add_u32 s100, s98, 0x1c800
	s_addc_u32 s101, s99, 0
	v_mov_b32_dpp v250, v78 quad_perm:[1,0,3,2] row_mask:0xf bank_mask:0xf bound_ctrl:1
	v_mov_b32_dpp v251, v80 quad_perm:[1,0,3,2] row_mask:0xf bank_mask:0xf bound_ctrl:1
	v_perm_b32 v78, v250, v78, v252
	v_perm_b32 v80, v251, v80, v252
	global_store_dword v244, v78, s[100:101] offset:-2048
	global_store_dword v244, v80, s[100:101] offset:2048
	s_cmp_eq_u32 s8, -2
	s_cbranch_scc1 .LBB0_965
